# RWKV step loop rewritten by hand: LDS operand prefetch one step ahead, output dot/reduction of step s-1 interleaved with S.a chain of step s
# baseline (speedup 1.0000x reference)
; DI float sum8(float v) { v += dpp_mov<0xB1>(v); v += dpp_mov<0x4E>(v); v += dpp_mov<0x141>(v); return v; }
; DI void rwkv_item(const Ctx& c, int item, char* smem) {
;     ...
; #pragma unroll 4
;     for (int s = 0; s < T; ++s) {
;       const float* o = op + s * 384 + kq * 8;
;       const f32x4 a0 = *(const f32x4*)(o + 128), a1 = *(const f32x4*)(o + 132);
;       const f32x2 av[4] = {(f32x2){a0[0], a0[1]}, (f32x2){a0[2], a0[3]}, (f32x2){a1[0], a1[1]}, (f32x2){a1[2], a1[3]}};
;       f32x2 t0 = S0[0] * av[0], t1 = S1[0] * av[0];
; #pragma unroll
;       for (int j = 1; j < 4; ++j) { t0 += S0[j] * av[j]; t1 += S1[j] * av[j]; }
;       float sa0 = t0[0] + t0[1], sa1 = t1[0] + t1[1];
;       sa0 = sum8(sa0); sa1 = sum8(sa1);
;       const f32x2 vv = *(const f32x2*)(op + s * 384 + 320 + rp * 2);
;       const f32x4 w0 = *(const f32x4*)(o), w1 = *(const f32x4*)(o + 4), k0 = *(const f32x4*)(o + 64), k1 = *(const f32x4*)(o + 68);
;       const f32x4 b0 = *(const f32x4*)(o + 192), b1 = *(const f32x4*)(o + 196), r0 = *(const f32x4*)(o + 256), r1 = *(const f32x4*)(o + 260);
;       const f32x2 wv[4] = {(f32x2){w0[0], w0[1]}, (f32x2){w0[2], w0[3]}, (f32x2){w1[0], w1[1]}, (f32x2){w1[2], w1[3]}};
;       const f32x2 kv[4] = {(f32x2){k0[0], k0[1]}, (f32x2){k0[2], k0[3]}, (f32x2){k1[0], k1[1]}, (f32x2){k1[2], k1[3]}};
;       const f32x2 bv[4] = {(f32x2){b0[0], b0[1]}, (f32x2){b0[2], b0[3]}, (f32x2){b1[0], b1[1]}, (f32x2){b1[2], b1[3]}};
;       const f32x2 rv[4] = {(f32x2){r0[0], r0[1]}, (f32x2){r0[2], r0[3]}, (f32x2){r1[0], r1[1]}, (f32x2){r1[2], r1[3]}};
;       f32x2 y0 = (f32x2){0.f, 0.f}, y1 = (f32x2){0.f, 0.f};
; #pragma unroll
;       for (int j = 0; j < 4; ++j) {
;         S0[j] = S0[j] * wv[j] + bv[j] * sa0 + kv[j] * vv[0];
;         S1[j] = S1[j] * wv[j] + bv[j] * sa1 + kv[j] * vv[1];
;         y0 += S0[j] * rv[j]; y1 += S1[j] * rv[j];
;       }
;       float ya = y0[0] + y0[1], yb = y1[0] + y1[1];
;       ya = sum8(ya); yb = sum8(yb);
;       if (kq == 0) *(f32x2*)(yo + s * 64 + rp * 2) = (f32x2){ya, yb};
;     }
.LBB0_802:
	s_mov_b32 s17, 0
	v_mov_b32_e32 v84, v59
	ds_read_b128 v[124:127], v61 offset:512
	ds_read_b128 v[128:131], v61 offset:528
	ds_read_b64 v[156:157], v62 offset:0
	ds_read_b128 v[132:135], v61 offset:0
	ds_read_b128 v[136:139], v61 offset:16
	ds_read_b128 v[148:151], v61 offset:768
	ds_read_b128 v[140:143], v61 offset:256
	ds_read_b128 v[144:147], v61 offset:272
	ds_read_b128 v[152:155], v61 offset:784
	ds_read_b128 v[196:199], v61 offset:1024
	ds_read_b128 v[200:203], v61 offset:1040
.LBB0_804:
	v_add_u32_e32 v85, s17, v61
	v_add_u32_e32 v86, s17, v62
	v_add_u32_e32 v250, 0xffffff00, v84
	ds_read_b128 v[158:161], v85 offset:2048
	ds_read_b128 v[162:165], v85 offset:2064
	ds_read_b64 v[190:191], v86 offset:1536
	ds_read_b128 v[166:169], v85 offset:1536
	ds_read_b128 v[170:173], v85 offset:1552
	ds_read_b128 v[182:185], v85 offset:2304
	ds_read_b128 v[174:177], v85 offset:1792
	ds_read_b128 v[178:181], v85 offset:1808
	ds_read_b128 v[186:189], v85 offset:2320
	ds_read_b128 v[204:207], v85 offset:2560
	ds_read_b128 v[208:211], v85 offset:2576
	s_waitcnt lgkmcnt(11)
	v_pk_mul_f32 v[228:229], v[16:17], v[126:127]
	v_pk_mul_f32 v[230:231], v[6:7], v[126:127]
	v_pk_fma_f32 v[232:233], v[220:221], v[12:13], 0 op_sel_hi:[1,1,0]
	v_pk_fma_f32 v[234:235], v[220:221], v[4:5], 0 op_sel_hi:[1,1,0]
	v_pk_fma_f32 v[228:229], v[12:13], v[124:125], v[228:229]
	v_pk_fma_f32 v[230:231], v[4:5], v[124:125], v[230:231]
	v_pk_fma_f32 v[232:233], v[222:223], v[16:17], v[232:233]
	v_pk_fma_f32 v[234:235], v[222:223], v[6:7], v[234:235]
	v_pk_fma_f32 v[228:229], v[14:15], v[128:129], v[228:229]
	v_pk_fma_f32 v[230:231], v[8:9], v[128:129], v[230:231]
	v_pk_fma_f32 v[232:233], v[224:225], v[14:15], v[232:233]
	v_pk_fma_f32 v[234:235], v[224:225], v[8:9], v[234:235]
	v_pk_fma_f32 v[228:229], v[18:19], v[130:131], v[228:229]
	v_pk_fma_f32 v[230:231], v[10:11], v[130:131], v[230:231]
	v_pk_fma_f32 v[232:233], v[226:227], v[18:19], v[232:233]
	v_pk_fma_f32 v[234:235], v[226:227], v[10:11], v[234:235]
	v_add_f32_e32 v244, v228, v229
	v_add_f32_e32 v245, v230, v231
	v_add_f32_e32 v246, v232, v233
	v_add_f32_e32 v247, v234, v235
	v_add_f32_dpp v248, v244, v244 quad_perm:[1,0,3,2] row_mask:0xf bank_mask:0xf bound_ctrl:1
	v_add_f32_dpp v249, v245, v245 quad_perm:[1,0,3,2] row_mask:0xf bank_mask:0xf bound_ctrl:1
	v_add_f32_dpp v246, v246, v246 quad_perm:[1,0,3,2] row_mask:0xf bank_mask:0xf bound_ctrl:1
	v_add_f32_dpp v247, v247, v247 quad_perm:[1,0,3,2] row_mask:0xf bank_mask:0xf bound_ctrl:1
	v_add_f32_dpp v248, v248, v248 quad_perm:[2,3,0,1] row_mask:0xf bank_mask:0xf bound_ctrl:1
	v_add_f32_dpp v249, v249, v249 quad_perm:[2,3,0,1] row_mask:0xf bank_mask:0xf bound_ctrl:1
	v_add_f32_dpp v246, v246, v246 quad_perm:[2,3,0,1] row_mask:0xf bank_mask:0xf bound_ctrl:1
	v_add_f32_dpp v247, v247, v247 quad_perm:[2,3,0,1] row_mask:0xf bank_mask:0xf bound_ctrl:1
	v_add_f32_dpp v236, v248, v248 row_half_mirror row_mask:0xf bank_mask:0xf bound_ctrl:1
	v_add_f32_dpp v238, v249, v249 row_half_mirror row_mask:0xf bank_mask:0xf bound_ctrl:1
	v_add_f32_dpp v246, v246, v246 row_half_mirror row_mask:0xf bank_mask:0xf bound_ctrl:1
	v_add_f32_dpp v247, v247, v247 row_half_mirror row_mask:0xf bank_mask:0xf bound_ctrl:1
	v_pk_mul_f32 v[240:241], v[236:237], v[148:149] op_sel_hi:[0,1]
	v_pk_mul_f32 v[242:243], v[238:239], v[148:149] op_sel_hi:[0,1]
	v_pk_fma_f32 v[12:13], v[12:13], v[132:133], v[240:241]
	v_pk_fma_f32 v[4:5], v[4:5], v[132:133], v[242:243]
	v_pk_fma_f32 v[12:13], v[156:157], v[140:141], v[12:13] op_sel_hi:[0,1,1]
	v_pk_fma_f32 v[4:5], v[156:157], v[140:141], v[4:5] op_sel:[1,0,0]
	s_cmp_eq_u32 s17, 0
	s_cbranch_scc1 .Lrw2_nowr
	s_and_saveexec_b64 s[12:13], s[4:5]
	ds_write_b64 v250, v[246:247]
	s_or_b64 exec, exec, s[12:13]
.Lrw2_nowr:
	v_pk_mul_f32 v[240:241], v[236:237], v[150:151] op_sel_hi:[0,1]
	v_pk_mul_f32 v[242:243], v[238:239], v[150:151] op_sel_hi:[0,1]
	v_pk_fma_f32 v[16:17], v[16:17], v[134:135], v[240:241]
	v_pk_fma_f32 v[6:7], v[6:7], v[134:135], v[242:243]
	v_pk_fma_f32 v[16:17], v[156:157], v[142:143], v[16:17] op_sel_hi:[0,1,1]
	v_pk_fma_f32 v[6:7], v[156:157], v[142:143], v[6:7] op_sel:[1,0,0]
	v_pk_mul_f32 v[240:241], v[236:237], v[152:153] op_sel_hi:[0,1]
	v_pk_mul_f32 v[242:243], v[238:239], v[152:153] op_sel_hi:[0,1]
	v_pk_fma_f32 v[14:15], v[14:15], v[136:137], v[240:241]
	v_pk_fma_f32 v[8:9], v[8:9], v[136:137], v[242:243]
	v_pk_fma_f32 v[14:15], v[156:157], v[144:145], v[14:15] op_sel_hi:[0,1,1]
	v_pk_fma_f32 v[8:9], v[156:157], v[144:145], v[8:9] op_sel:[1,0,0]
	v_pk_mul_f32 v[240:241], v[236:237], v[154:155] op_sel_hi:[0,1]
	v_pk_mul_f32 v[242:243], v[238:239], v[154:155] op_sel_hi:[0,1]
	v_pk_fma_f32 v[18:19], v[18:19], v[138:139], v[240:241]
	v_pk_fma_f32 v[10:11], v[10:11], v[138:139], v[242:243]
	v_pk_fma_f32 v[18:19], v[156:157], v[146:147], v[18:19] op_sel_hi:[0,1,1]
	v_pk_fma_f32 v[10:11], v[156:157], v[146:147], v[10:11] op_sel:[1,0,0]
	ds_read_b128 v[124:127], v85 offset:3584
	ds_read_b128 v[128:131], v85 offset:3600
	ds_read_b64 v[156:157], v86 offset:3072
	ds_read_b128 v[132:135], v85 offset:3072
	ds_read_b128 v[136:139], v85 offset:3088
	ds_read_b128 v[148:151], v85 offset:3840
	ds_read_b128 v[140:143], v85 offset:3328
	ds_read_b128 v[144:147], v85 offset:3344
	ds_read_b128 v[152:155], v85 offset:3856
	ds_read_b128 v[212:215], v85 offset:4096
	ds_read_b128 v[216:219], v85 offset:4112
	s_waitcnt lgkmcnt(11)
; DI float sum8(float v) { v += dpp_mov<0xB1>(v); v += dpp_mov<0x4E>(v); v += dpp_mov<0x141>(v); return v; }
; DI void rwkv_item(const Ctx& c, int item, char* smem) {
;     ...
; #pragma unroll 4
;     for (int s = 0; s < T; ++s) {
;       const float* o = op + s * 384 + kq * 8;
;       const f32x4 a0 = *(const f32x4*)(o + 128), a1 = *(const f32x4*)(o + 132);
;       const f32x2 av[4] = {(f32x2){a0[0], a0[1]}, (f32x2){a0[2], a0[3]}, (f32x2){a1[0], a1[1]}, (f32x2){a1[2], a1[3]}};
;       f32x2 t0 = S0[0] * av[0], t1 = S1[0] * av[0];
; #pragma unroll
;       for (int j = 1; j < 4; ++j) { t0 += S0[j] * av[j]; t1 += S1[j] * av[j]; }
;       float sa0 = t0[0] + t0[1], sa1 = t1[0] + t1[1];
;       sa0 = sum8(sa0); sa1 = sum8(sa1);
;       const f32x2 vv = *(const f32x2*)(op + s * 384 + 320 + rp * 2);
;       const f32x4 w0 = *(const f32x4*)(o), w1 = *(const f32x4*)(o + 4), k0 = *(const f32x4*)(o + 64), k1 = *(const f32x4*)(o + 68);
;       const f32x4 b0 = *(const f32x4*)(o + 192), b1 = *(const f32x4*)(o + 196), r0 = *(const f32x4*)(o + 256), r1 = *(const f32x4*)(o + 260);
;       const f32x2 wv[4] = {(f32x2){w0[0], w0[1]}, (f32x2){w0[2], w0[3]}, (f32x2){w1[0], w1[1]}, (f32x2){w1[2], w1[3]}};
;       const f32x2 kv[4] = {(f32x2){k0[0], k0[1]}, (f32x2){k0[2], k0[3]}, (f32x2){k1[0], k1[1]}, (f32x2){k1[2], k1[3]}};
;       const f32x2 bv[4] = {(f32x2){b0[0], b0[1]}, (f32x2){b0[2], b0[3]}, (f32x2){b1[0], b1[1]}, (f32x2){b1[2], b1[3]}};
;       const f32x2 rv[4] = {(f32x2){r0[0], r0[1]}, (f32x2){r0[2], r0[3]}, (f32x2){r1[0], r1[1]}, (f32x2){r1[2], r1[3]}};
;       f32x2 y0 = (f32x2){0.f, 0.f}, y1 = (f32x2){0.f, 0.f};
; #pragma unroll
;       for (int j = 0; j < 4; ++j) {
;         S0[j] = S0[j] * wv[j] + bv[j] * sa0 + kv[j] * vv[0];
;         S1[j] = S1[j] * wv[j] + bv[j] * sa1 + kv[j] * vv[1];
;         y0 += S0[j] * rv[j]; y1 += S1[j] * rv[j];
;       }
;       float ya = y0[0] + y0[1], yb = y1[0] + y1[1];
;       ya = sum8(ya); yb = sum8(yb);
;       if (kq == 0) *(f32x2*)(yo + s * 64 + rp * 2) = (f32x2){ya, yb};
;     }
	v_pk_mul_f32 v[228:229], v[16:17], v[160:161]
	v_pk_mul_f32 v[230:231], v[6:7], v[160:161]
	v_pk_fma_f32 v[232:233], v[196:197], v[12:13], 0 op_sel_hi:[1,1,0]
	v_pk_fma_f32 v[234:235], v[196:197], v[4:5], 0 op_sel_hi:[1,1,0]
	v_pk_fma_f32 v[228:229], v[12:13], v[158:159], v[228:229]
	v_pk_fma_f32 v[230:231], v[4:5], v[158:159], v[230:231]
	v_pk_fma_f32 v[232:233], v[198:199], v[16:17], v[232:233]
	v_pk_fma_f32 v[234:235], v[198:199], v[6:7], v[234:235]
	v_pk_fma_f32 v[228:229], v[14:15], v[162:163], v[228:229]
	v_pk_fma_f32 v[230:231], v[8:9], v[162:163], v[230:231]
	v_pk_fma_f32 v[232:233], v[200:201], v[14:15], v[232:233]
	v_pk_fma_f32 v[234:235], v[200:201], v[8:9], v[234:235]
	v_pk_fma_f32 v[228:229], v[18:19], v[164:165], v[228:229]
	v_pk_fma_f32 v[230:231], v[10:11], v[164:165], v[230:231]
	v_pk_fma_f32 v[232:233], v[202:203], v[18:19], v[232:233]
	v_pk_fma_f32 v[234:235], v[202:203], v[10:11], v[234:235]
	v_add_f32_e32 v244, v228, v229
	v_add_f32_e32 v245, v230, v231
	v_add_f32_e32 v246, v232, v233
	v_add_f32_e32 v247, v234, v235
	v_add_f32_dpp v248, v244, v244 quad_perm:[1,0,3,2] row_mask:0xf bank_mask:0xf bound_ctrl:1
	v_add_f32_dpp v249, v245, v245 quad_perm:[1,0,3,2] row_mask:0xf bank_mask:0xf bound_ctrl:1
	v_add_f32_dpp v246, v246, v246 quad_perm:[1,0,3,2] row_mask:0xf bank_mask:0xf bound_ctrl:1
	v_add_f32_dpp v247, v247, v247 quad_perm:[1,0,3,2] row_mask:0xf bank_mask:0xf bound_ctrl:1
	v_add_f32_dpp v248, v248, v248 quad_perm:[2,3,0,1] row_mask:0xf bank_mask:0xf bound_ctrl:1
	v_add_f32_dpp v249, v249, v249 quad_perm:[2,3,0,1] row_mask:0xf bank_mask:0xf bound_ctrl:1
	v_add_f32_dpp v246, v246, v246 quad_perm:[2,3,0,1] row_mask:0xf bank_mask:0xf bound_ctrl:1
	v_add_f32_dpp v247, v247, v247 quad_perm:[2,3,0,1] row_mask:0xf bank_mask:0xf bound_ctrl:1
	v_add_f32_dpp v236, v248, v248 row_half_mirror row_mask:0xf bank_mask:0xf bound_ctrl:1
	v_add_f32_dpp v238, v249, v249 row_half_mirror row_mask:0xf bank_mask:0xf bound_ctrl:1
	v_add_f32_dpp v246, v246, v246 row_half_mirror row_mask:0xf bank_mask:0xf bound_ctrl:1
	v_add_f32_dpp v247, v247, v247 row_half_mirror row_mask:0xf bank_mask:0xf bound_ctrl:1
	v_pk_mul_f32 v[240:241], v[236:237], v[182:183] op_sel_hi:[0,1]
	v_pk_mul_f32 v[242:243], v[238:239], v[182:183] op_sel_hi:[0,1]
	v_pk_fma_f32 v[12:13], v[12:13], v[166:167], v[240:241]
	v_pk_fma_f32 v[4:5], v[4:5], v[166:167], v[242:243]
	v_pk_fma_f32 v[12:13], v[190:191], v[174:175], v[12:13] op_sel_hi:[0,1,1]
	v_pk_fma_f32 v[4:5], v[190:191], v[174:175], v[4:5] op_sel:[1,0,0]
	s_and_saveexec_b64 s[12:13], s[4:5]
	ds_write_b64 v84, v[246:247]
	s_or_b64 exec, exec, s[12:13]
	v_pk_mul_f32 v[240:241], v[236:237], v[184:185] op_sel_hi:[0,1]
	v_pk_mul_f32 v[242:243], v[238:239], v[184:185] op_sel_hi:[0,1]
	v_pk_fma_f32 v[16:17], v[16:17], v[168:169], v[240:241]
	v_pk_fma_f32 v[6:7], v[6:7], v[168:169], v[242:243]
	v_pk_fma_f32 v[16:17], v[190:191], v[176:177], v[16:17] op_sel_hi:[0,1,1]
	v_pk_fma_f32 v[6:7], v[190:191], v[176:177], v[6:7] op_sel:[1,0,0]
	v_pk_mul_f32 v[240:241], v[236:237], v[186:187] op_sel_hi:[0,1]
	v_pk_mul_f32 v[242:243], v[238:239], v[186:187] op_sel_hi:[0,1]
	v_pk_fma_f32 v[14:15], v[14:15], v[170:171], v[240:241]
	v_pk_fma_f32 v[8:9], v[8:9], v[170:171], v[242:243]
	v_pk_fma_f32 v[14:15], v[190:191], v[178:179], v[14:15] op_sel_hi:[0,1,1]
	v_pk_fma_f32 v[8:9], v[190:191], v[178:179], v[8:9] op_sel:[1,0,0]
	v_pk_mul_f32 v[240:241], v[236:237], v[188:189] op_sel_hi:[0,1]
	v_pk_mul_f32 v[242:243], v[238:239], v[188:189] op_sel_hi:[0,1]
	v_pk_fma_f32 v[18:19], v[18:19], v[172:173], v[240:241]
	v_pk_fma_f32 v[10:11], v[10:11], v[172:173], v[242:243]
	v_pk_fma_f32 v[18:19], v[190:191], v[180:181], v[18:19] op_sel_hi:[0,1,1]
	v_pk_fma_f32 v[10:11], v[190:191], v[180:181], v[10:11] op_sel:[1,0,0]
	ds_read_b128 v[158:161], v85 offset:5120
	ds_read_b128 v[162:165], v85 offset:5136
	ds_read_b64 v[190:191], v86 offset:4608
	ds_read_b128 v[166:169], v85 offset:4608
	ds_read_b128 v[170:173], v85 offset:4624
	ds_read_b128 v[182:185], v85 offset:5376
	ds_read_b128 v[174:177], v85 offset:4864
	ds_read_b128 v[178:181], v85 offset:4880
	ds_read_b128 v[186:189], v85 offset:5392
	ds_read_b128 v[220:223], v85 offset:5632
	ds_read_b128 v[224:227], v85 offset:5648
	s_waitcnt lgkmcnt(12)
; DI float sum8(float v) { v += dpp_mov<0xB1>(v); v += dpp_mov<0x4E>(v); v += dpp_mov<0x141>(v); return v; }
; DI void rwkv_item(const Ctx& c, int item, char* smem) {
;     ...
; #pragma unroll 4
;     for (int s = 0; s < T; ++s) {
;       const float* o = op + s * 384 + kq * 8;
;       const f32x4 a0 = *(const f32x4*)(o + 128), a1 = *(const f32x4*)(o + 132);
;       const f32x2 av[4] = {(f32x2){a0[0], a0[1]}, (f32x2){a0[2], a0[3]}, (f32x2){a1[0], a1[1]}, (f32x2){a1[2], a1[3]}};
;       f32x2 t0 = S0[0] * av[0], t1 = S1[0] * av[0];
; #pragma unroll
;       for (int j = 1; j < 4; ++j) { t0 += S0[j] * av[j]; t1 += S1[j] * av[j]; }
;       float sa0 = t0[0] + t0[1], sa1 = t1[0] + t1[1];
;       sa0 = sum8(sa0); sa1 = sum8(sa1);
;       const f32x2 vv = *(const f32x2*)(op + s * 384 + 320 + rp * 2);
;       const f32x4 w0 = *(const f32x4*)(o), w1 = *(const f32x4*)(o + 4), k0 = *(const f32x4*)(o + 64), k1 = *(const f32x4*)(o + 68);
;       const f32x4 b0 = *(const f32x4*)(o + 192), b1 = *(const f32x4*)(o + 196), r0 = *(const f32x4*)(o + 256), r1 = *(const f32x4*)(o + 260);
;       const f32x2 wv[4] = {(f32x2){w0[0], w0[1]}, (f32x2){w0[2], w0[3]}, (f32x2){w1[0], w1[1]}, (f32x2){w1[2], w1[3]}};
;       const f32x2 kv[4] = {(f32x2){k0[0], k0[1]}, (f32x2){k0[2], k0[3]}, (f32x2){k1[0], k1[1]}, (f32x2){k1[2], k1[3]}};
;       const f32x2 bv[4] = {(f32x2){b0[0], b0[1]}, (f32x2){b0[2], b0[3]}, (f32x2){b1[0], b1[1]}, (f32x2){b1[2], b1[3]}};
;       const f32x2 rv[4] = {(f32x2){r0[0], r0[1]}, (f32x2){r0[2], r0[3]}, (f32x2){r1[0], r1[1]}, (f32x2){r1[2], r1[3]}};
;       f32x2 y0 = (f32x2){0.f, 0.f}, y1 = (f32x2){0.f, 0.f};
; #pragma unroll
;       for (int j = 0; j < 4; ++j) {
;         S0[j] = S0[j] * wv[j] + bv[j] * sa0 + kv[j] * vv[0];
;         S1[j] = S1[j] * wv[j] + bv[j] * sa1 + kv[j] * vv[1];
;         y0 += S0[j] * rv[j]; y1 += S1[j] * rv[j];
;       }
;       float ya = y0[0] + y0[1], yb = y1[0] + y1[1];
;       ya = sum8(ya); yb = sum8(yb);
;       if (kq == 0) *(f32x2*)(yo + s * 64 + rp * 2) = (f32x2){ya, yb};
;     }
	v_pk_mul_f32 v[228:229], v[16:17], v[126:127]
	v_pk_mul_f32 v[230:231], v[6:7], v[126:127]
	v_pk_fma_f32 v[232:233], v[204:205], v[12:13], 0 op_sel_hi:[1,1,0]
	v_pk_fma_f32 v[234:235], v[204:205], v[4:5], 0 op_sel_hi:[1,1,0]
	v_pk_fma_f32 v[228:229], v[12:13], v[124:125], v[228:229]
	v_pk_fma_f32 v[230:231], v[4:5], v[124:125], v[230:231]
	v_pk_fma_f32 v[232:233], v[206:207], v[16:17], v[232:233]
	v_pk_fma_f32 v[234:235], v[206:207], v[6:7], v[234:235]
	v_pk_fma_f32 v[228:229], v[14:15], v[128:129], v[228:229]
	v_pk_fma_f32 v[230:231], v[8:9], v[128:129], v[230:231]
	v_pk_fma_f32 v[232:233], v[208:209], v[14:15], v[232:233]
	v_pk_fma_f32 v[234:235], v[208:209], v[8:9], v[234:235]
	v_pk_fma_f32 v[228:229], v[18:19], v[130:131], v[228:229]
	v_pk_fma_f32 v[230:231], v[10:11], v[130:131], v[230:231]
	v_pk_fma_f32 v[232:233], v[210:211], v[18:19], v[232:233]
	v_pk_fma_f32 v[234:235], v[210:211], v[10:11], v[234:235]
	v_add_f32_e32 v244, v228, v229
	v_add_f32_e32 v245, v230, v231
	v_add_f32_e32 v246, v232, v233
	v_add_f32_e32 v247, v234, v235
	v_add_f32_dpp v248, v244, v244 quad_perm:[1,0,3,2] row_mask:0xf bank_mask:0xf bound_ctrl:1
	v_add_f32_dpp v249, v245, v245 quad_perm:[1,0,3,2] row_mask:0xf bank_mask:0xf bound_ctrl:1
	v_add_f32_dpp v246, v246, v246 quad_perm:[1,0,3,2] row_mask:0xf bank_mask:0xf bound_ctrl:1
	v_add_f32_dpp v247, v247, v247 quad_perm:[1,0,3,2] row_mask:0xf bank_mask:0xf bound_ctrl:1
	v_add_f32_dpp v248, v248, v248 quad_perm:[2,3,0,1] row_mask:0xf bank_mask:0xf bound_ctrl:1
	v_add_f32_dpp v249, v249, v249 quad_perm:[2,3,0,1] row_mask:0xf bank_mask:0xf bound_ctrl:1
	v_add_f32_dpp v246, v246, v246 quad_perm:[2,3,0,1] row_mask:0xf bank_mask:0xf bound_ctrl:1
	v_add_f32_dpp v247, v247, v247 quad_perm:[2,3,0,1] row_mask:0xf bank_mask:0xf bound_ctrl:1
	v_add_f32_dpp v236, v248, v248 row_half_mirror row_mask:0xf bank_mask:0xf bound_ctrl:1
	v_add_f32_dpp v238, v249, v249 row_half_mirror row_mask:0xf bank_mask:0xf bound_ctrl:1
	v_add_f32_dpp v246, v246, v246 row_half_mirror row_mask:0xf bank_mask:0xf bound_ctrl:1
	v_add_f32_dpp v247, v247, v247 row_half_mirror row_mask:0xf bank_mask:0xf bound_ctrl:1
	v_pk_mul_f32 v[240:241], v[236:237], v[148:149] op_sel_hi:[0,1]
	v_pk_mul_f32 v[242:243], v[238:239], v[148:149] op_sel_hi:[0,1]
	v_pk_fma_f32 v[12:13], v[12:13], v[132:133], v[240:241]
	v_pk_fma_f32 v[4:5], v[4:5], v[132:133], v[242:243]
	v_pk_fma_f32 v[12:13], v[156:157], v[140:141], v[12:13] op_sel_hi:[0,1,1]
	v_pk_fma_f32 v[4:5], v[156:157], v[140:141], v[4:5] op_sel:[1,0,0]
	s_and_saveexec_b64 s[12:13], s[4:5]
	ds_write_b64 v84, v[246:247] offset:256
	s_or_b64 exec, exec, s[12:13]
	v_pk_mul_f32 v[240:241], v[236:237], v[150:151] op_sel_hi:[0,1]
	v_pk_mul_f32 v[242:243], v[238:239], v[150:151] op_sel_hi:[0,1]
	v_pk_fma_f32 v[16:17], v[16:17], v[134:135], v[240:241]
	v_pk_fma_f32 v[6:7], v[6:7], v[134:135], v[242:243]
	v_pk_fma_f32 v[16:17], v[156:157], v[142:143], v[16:17] op_sel_hi:[0,1,1]
	v_pk_fma_f32 v[6:7], v[156:157], v[142:143], v[6:7] op_sel:[1,0,0]
	v_pk_mul_f32 v[240:241], v[236:237], v[152:153] op_sel_hi:[0,1]
	v_pk_mul_f32 v[242:243], v[238:239], v[152:153] op_sel_hi:[0,1]
	v_pk_fma_f32 v[14:15], v[14:15], v[136:137], v[240:241]
	v_pk_fma_f32 v[8:9], v[8:9], v[136:137], v[242:243]
	v_pk_fma_f32 v[14:15], v[156:157], v[144:145], v[14:15] op_sel_hi:[0,1,1]
	v_pk_fma_f32 v[8:9], v[156:157], v[144:145], v[8:9] op_sel:[1,0,0]
	v_pk_mul_f32 v[240:241], v[236:237], v[154:155] op_sel_hi:[0,1]
	v_pk_mul_f32 v[242:243], v[238:239], v[154:155] op_sel_hi:[0,1]
	v_pk_fma_f32 v[18:19], v[18:19], v[138:139], v[240:241]
	v_pk_fma_f32 v[10:11], v[10:11], v[138:139], v[242:243]
	v_pk_fma_f32 v[18:19], v[156:157], v[146:147], v[18:19] op_sel_hi:[0,1,1]
	v_pk_fma_f32 v[10:11], v[156:157], v[146:147], v[10:11] op_sel:[1,0,0]
	ds_read_b128 v[124:127], v85 offset:6656
	ds_read_b128 v[128:131], v85 offset:6672
	ds_read_b64 v[156:157], v86 offset:6144
	ds_read_b128 v[132:135], v85 offset:6144
	ds_read_b128 v[136:139], v85 offset:6160
	ds_read_b128 v[148:151], v85 offset:6912
	ds_read_b128 v[140:143], v85 offset:6400
	ds_read_b128 v[144:147], v85 offset:6416
	ds_read_b128 v[152:155], v85 offset:6928
	ds_read_b128 v[196:199], v85 offset:7168
	ds_read_b128 v[200:203], v85 offset:7184
	s_waitcnt lgkmcnt(12)
; DI float sum8(float v) { v += dpp_mov<0xB1>(v); v += dpp_mov<0x4E>(v); v += dpp_mov<0x141>(v); return v; }
; DI void rwkv_item(const Ctx& c, int item, char* smem) {
;     ...
; #pragma unroll 4
;     for (int s = 0; s < T; ++s) {
;       const float* o = op + s * 384 + kq * 8;
;       const f32x4 a0 = *(const f32x4*)(o + 128), a1 = *(const f32x4*)(o + 132);
;       const f32x2 av[4] = {(f32x2){a0[0], a0[1]}, (f32x2){a0[2], a0[3]}, (f32x2){a1[0], a1[1]}, (f32x2){a1[2], a1[3]}};
;       f32x2 t0 = S0[0] * av[0], t1 = S1[0] * av[0];
; #pragma unroll
;       for (int j = 1; j < 4; ++j) { t0 += S0[j] * av[j]; t1 += S1[j] * av[j]; }
;       float sa0 = t0[0] + t0[1], sa1 = t1[0] + t1[1];
;       sa0 = sum8(sa0); sa1 = sum8(sa1);
;       const f32x2 vv = *(const f32x2*)(op + s * 384 + 320 + rp * 2);
;       const f32x4 w0 = *(const f32x4*)(o), w1 = *(const f32x4*)(o + 4), k0 = *(const f32x4*)(o + 64), k1 = *(const f32x4*)(o + 68);
;       const f32x4 b0 = *(const f32x4*)(o + 192), b1 = *(const f32x4*)(o + 196), r0 = *(const f32x4*)(o + 256), r1 = *(const f32x4*)(o + 260);
;       const f32x2 wv[4] = {(f32x2){w0[0], w0[1]}, (f32x2){w0[2], w0[3]}, (f32x2){w1[0], w1[1]}, (f32x2){w1[2], w1[3]}};
;       const f32x2 kv[4] = {(f32x2){k0[0], k0[1]}, (f32x2){k0[2], k0[3]}, (f32x2){k1[0], k1[1]}, (f32x2){k1[2], k1[3]}};
;       const f32x2 bv[4] = {(f32x2){b0[0], b0[1]}, (f32x2){b0[2], b0[3]}, (f32x2){b1[0], b1[1]}, (f32x2){b1[2], b1[3]}};
;       const f32x2 rv[4] = {(f32x2){r0[0], r0[1]}, (f32x2){r0[2], r0[3]}, (f32x2){r1[0], r1[1]}, (f32x2){r1[2], r1[3]}};
;       f32x2 y0 = (f32x2){0.f, 0.f}, y1 = (f32x2){0.f, 0.f};
; #pragma unroll
;       for (int j = 0; j < 4; ++j) {
;         S0[j] = S0[j] * wv[j] + bv[j] * sa0 + kv[j] * vv[0];
;         S1[j] = S1[j] * wv[j] + bv[j] * sa1 + kv[j] * vv[1];
;         y0 += S0[j] * rv[j]; y1 += S1[j] * rv[j];
;       }
;       float ya = y0[0] + y0[1], yb = y1[0] + y1[1];
;       ya = sum8(ya); yb = sum8(yb);
;       if (kq == 0) *(f32x2*)(yo + s * 64 + rp * 2) = (f32x2){ya, yb};
;     }
	v_pk_mul_f32 v[228:229], v[16:17], v[160:161]
	v_pk_mul_f32 v[230:231], v[6:7], v[160:161]
	v_pk_fma_f32 v[232:233], v[212:213], v[12:13], 0 op_sel_hi:[1,1,0]
	v_pk_fma_f32 v[234:235], v[212:213], v[4:5], 0 op_sel_hi:[1,1,0]
	v_pk_fma_f32 v[228:229], v[12:13], v[158:159], v[228:229]
	v_pk_fma_f32 v[230:231], v[4:5], v[158:159], v[230:231]
	v_pk_fma_f32 v[232:233], v[214:215], v[16:17], v[232:233]
	v_pk_fma_f32 v[234:235], v[214:215], v[6:7], v[234:235]
	v_pk_fma_f32 v[228:229], v[14:15], v[162:163], v[228:229]
	v_pk_fma_f32 v[230:231], v[8:9], v[162:163], v[230:231]
	v_pk_fma_f32 v[232:233], v[216:217], v[14:15], v[232:233]
	v_pk_fma_f32 v[234:235], v[216:217], v[8:9], v[234:235]
	v_pk_fma_f32 v[228:229], v[18:19], v[164:165], v[228:229]
	v_pk_fma_f32 v[230:231], v[10:11], v[164:165], v[230:231]
	v_pk_fma_f32 v[232:233], v[218:219], v[18:19], v[232:233]
	v_pk_fma_f32 v[234:235], v[218:219], v[10:11], v[234:235]
	v_add_f32_e32 v244, v228, v229
	v_add_f32_e32 v245, v230, v231
	v_add_f32_e32 v246, v232, v233
	v_add_f32_e32 v247, v234, v235
	v_add_f32_dpp v248, v244, v244 quad_perm:[1,0,3,2] row_mask:0xf bank_mask:0xf bound_ctrl:1
	v_add_f32_dpp v249, v245, v245 quad_perm:[1,0,3,2] row_mask:0xf bank_mask:0xf bound_ctrl:1
	v_add_f32_dpp v246, v246, v246 quad_perm:[1,0,3,2] row_mask:0xf bank_mask:0xf bound_ctrl:1
	v_add_f32_dpp v247, v247, v247 quad_perm:[1,0,3,2] row_mask:0xf bank_mask:0xf bound_ctrl:1
	v_add_f32_dpp v248, v248, v248 quad_perm:[2,3,0,1] row_mask:0xf bank_mask:0xf bound_ctrl:1
	v_add_f32_dpp v249, v249, v249 quad_perm:[2,3,0,1] row_mask:0xf bank_mask:0xf bound_ctrl:1
	v_add_f32_dpp v246, v246, v246 quad_perm:[2,3,0,1] row_mask:0xf bank_mask:0xf bound_ctrl:1
	v_add_f32_dpp v247, v247, v247 quad_perm:[2,3,0,1] row_mask:0xf bank_mask:0xf bound_ctrl:1
	v_add_f32_dpp v236, v248, v248 row_half_mirror row_mask:0xf bank_mask:0xf bound_ctrl:1
	v_add_f32_dpp v238, v249, v249 row_half_mirror row_mask:0xf bank_mask:0xf bound_ctrl:1
	v_add_f32_dpp v246, v246, v246 row_half_mirror row_mask:0xf bank_mask:0xf bound_ctrl:1
	v_add_f32_dpp v247, v247, v247 row_half_mirror row_mask:0xf bank_mask:0xf bound_ctrl:1
	v_pk_mul_f32 v[240:241], v[236:237], v[182:183] op_sel_hi:[0,1]
	v_pk_mul_f32 v[242:243], v[238:239], v[182:183] op_sel_hi:[0,1]
	v_pk_fma_f32 v[12:13], v[12:13], v[166:167], v[240:241]
	v_pk_fma_f32 v[4:5], v[4:5], v[166:167], v[242:243]
	v_pk_fma_f32 v[12:13], v[190:191], v[174:175], v[12:13] op_sel_hi:[0,1,1]
	v_pk_fma_f32 v[4:5], v[190:191], v[174:175], v[4:5] op_sel:[1,0,0]
	s_and_saveexec_b64 s[12:13], s[4:5]
	ds_write_b64 v84, v[246:247] offset:512
	s_or_b64 exec, exec, s[12:13]
	v_pk_mul_f32 v[240:241], v[236:237], v[184:185] op_sel_hi:[0,1]
	v_pk_mul_f32 v[242:243], v[238:239], v[184:185] op_sel_hi:[0,1]
	v_pk_fma_f32 v[16:17], v[16:17], v[168:169], v[240:241]
	v_pk_fma_f32 v[6:7], v[6:7], v[168:169], v[242:243]
	v_pk_fma_f32 v[16:17], v[190:191], v[176:177], v[16:17] op_sel_hi:[0,1,1]
	v_pk_fma_f32 v[6:7], v[190:191], v[176:177], v[6:7] op_sel:[1,0,0]
	v_pk_mul_f32 v[240:241], v[236:237], v[186:187] op_sel_hi:[0,1]
	v_pk_mul_f32 v[242:243], v[238:239], v[186:187] op_sel_hi:[0,1]
	v_pk_fma_f32 v[14:15], v[14:15], v[170:171], v[240:241]
	v_pk_fma_f32 v[8:9], v[8:9], v[170:171], v[242:243]
	v_pk_fma_f32 v[14:15], v[190:191], v[178:179], v[14:15] op_sel_hi:[0,1,1]
	v_pk_fma_f32 v[8:9], v[190:191], v[178:179], v[8:9] op_sel:[1,0,0]
	v_pk_mul_f32 v[240:241], v[236:237], v[188:189] op_sel_hi:[0,1]
	v_pk_mul_f32 v[242:243], v[238:239], v[188:189] op_sel_hi:[0,1]
	v_pk_fma_f32 v[18:19], v[18:19], v[172:173], v[240:241]
	v_pk_fma_f32 v[10:11], v[10:11], v[172:173], v[242:243]
	v_pk_fma_f32 v[18:19], v[190:191], v[180:181], v[18:19] op_sel_hi:[0,1,1]
	v_pk_fma_f32 v[10:11], v[190:191], v[180:181], v[10:11] op_sel:[1,0,0]
	s_addk_i32 s17, 0x1800
	s_cmpk_eq_u32 s17, 0xc000
	v_add_u32_e32 v84, 0x400, v84
	s_cbranch_scc0 .LBB0_804
	v_add_u32_e32 v250, 0xffffff00, v84
	s_waitcnt lgkmcnt(0)
	v_pk_fma_f32 v[232:233], v[220:221], v[12:13], 0 op_sel_hi:[1,1,0]
	v_pk_fma_f32 v[234:235], v[220:221], v[4:5], 0 op_sel_hi:[1,1,0]
	v_pk_fma_f32 v[232:233], v[222:223], v[16:17], v[232:233]
	v_pk_fma_f32 v[234:235], v[222:223], v[6:7], v[234:235]
	v_pk_fma_f32 v[232:233], v[224:225], v[14:15], v[232:233]
	v_pk_fma_f32 v[234:235], v[224:225], v[8:9], v[234:235]
	v_pk_fma_f32 v[232:233], v[226:227], v[18:19], v[232:233]
	v_pk_fma_f32 v[234:235], v[226:227], v[10:11], v[234:235]
	v_add_f32_e32 v246, v232, v233
	v_add_f32_e32 v247, v234, v235
	s_nop 1
	v_add_f32_dpp v246, v246, v246 quad_perm:[1,0,3,2] row_mask:0xf bank_mask:0xf bound_ctrl:1
	v_add_f32_dpp v247, v247, v247 quad_perm:[1,0,3,2] row_mask:0xf bank_mask:0xf bound_ctrl:1
	s_nop 1
	v_add_f32_dpp v246, v246, v246 quad_perm:[2,3,0,1] row_mask:0xf bank_mask:0xf bound_ctrl:1
	v_add_f32_dpp v247, v247, v247 quad_perm:[2,3,0,1] row_mask:0xf bank_mask:0xf bound_ctrl:1
	s_nop 1
	v_add_f32_dpp v246, v246, v246 row_half_mirror row_mask:0xf bank_mask:0xf bound_ctrl:1
	v_add_f32_dpp v247, v247, v247 row_half_mirror row_mask:0xf bank_mask:0xf bound_ctrl:1
	s_nop 1
	s_and_saveexec_b64 s[12:13], s[4:5]
	ds_write_b64 v250, v[246:247]
	s_or_b64 exec, exec, s[12:13]
	s_branch .LBB0_799
